# in-proj GEMM: LDS-DMA loads use the scalar-base + 32-bit lane offset form (16 64-bit VALU address adds per K-iteration removed)
# speedup vs baseline: 1.0079x; 1.0079x over previous
; #define PG8_STAGE(bufoff, gbase, voff) do { _Pragma("unroll") for (int _i = 0; _i < 2; ++_i) \
;         __builtin_amdgcn_global_load_lds((const unsigned*)((const char*)(gbase) + (voff)[_i]), (LAS unsigned*)(lds + (bufoff) + ldsw + _i * 8192), 16, 0, 0); } while (0)
; #define PG8_LDA(dst, b, h) do { _Pragma("unroll") for (int m = 0; m < 4; ++m) _Pragma("unroll") for (int k = 0; k < 2; ++k) dst[m][k] = *(const LAS bf16x8*)(lds + PG8_SA(b, h) + aoff + m * 2048 + k * 1024); } while (0)
; template <class Epi>
; DI void gemm_phase(LAS unsigned char* lds, const Gemm g, const StaticOrder& S, const Epi& E, const int tid) {
;     ...
;     Unit cur, nxt; int ui = 0;
;     if (!S.next(0, cur)) return;
;     f32x4 acc[2][2][4][2];
; #pragma unroll
;     for (int a = 0; a < 2; ++a)
; #pragma unroll
;         for (int b = 0; b < 2; ++b)
; #pragma unroll
;             for (int m = 0; m < 4; ++m)
; #pragma unroll
;                 for (int n = 0; n < 2; ++n) acc[a][b][m][n] = (f32x4){0.f, 0.f, 0.f, 0.f};
;     bf16x8 At[4][2], B0[2][2], B1[2][2];
;     const char* cA = (const char*)g.A + (size_t)cur.pm * tstepA; const char* cB = (const char*)g.Bt + (size_t)cur.pn * tstepB;
;     PG8_STAGE(PG8_SB(0, 0), cB, voffB); PG8_STAGE(PG8_SA(0, 0), cA, voffA); PG8_STAGE(PG8_SB(0, 1), cB + hstepB, voffB); PG8_STAGE(PG8_SA(0, 1), cA + hstepA, voffA);
;     if (wr == 1) PG8_BAR;
;     PG8_WAIT_V(4); PG8_BAR;
;     PG8_STAGE(PG8_SB(1, 0), cB + kstep, voffB); PG8_STAGE(PG8_SA(1, 0), cA + PG8_KTA(1), voffA); PG8_STAGE(PG8_SB(1, 1), cB + hstepB + kstep, voffB);
;     PG8_WAIT_V(6); PG8_BAR;
;     for (;;) {
;         const bool has_next = S.next(ui + 1, nxt);
;         const char* nA = has_next ? (const char*)g.A + (size_t)nxt.pm * tstepA : cA; const char* nB = has_next ? (const char*)g.Bt + (size_t)nxt.pn * tstepB : cB;
;         for (int t = 0; t < nt; t += 2) {
;             const bool last = (t == nt - 2);
;             const char* a1 = cA + PG8_KTA(t + 1);
;             const char* a2 = last ? nA : cA + PG8_KTA(t + 2); const char* b2 = last ? nB : cB + (size_t)(t + 2) * kstep;
;             const char* a3 = last ? nA + PG8_KTA(1) : cA + PG8_KTA(t + 3); const char* b3 = b2 + kstep;
;             PG8_LDB(B0, 0, 0); PG8_SCHED; PG8_LDA(At, 0, 0); PG8_STAGE(PG8_SA(1, 1), a1 + hstepA, voffA);
;             PG8_WAIT_L(8); PG8_BAR; PG8_WAIT_L(0); PG8_MMA(0, 0, At, B0); PG8_BAR; PG8_SCHED;
.LBB0_61:
	s_ashr_i32 s43, s42, 31
	v_cmp_lt_i64_e32 vcc, s[6:7], v[142:143]
	s_lshl_b64 s[6:7], s[42:43], 20
	s_add_u32 s46, s70, s6
	s_addc_u32 s47, s71, s7
	s_and_b64 s[6:7], vcc, exec
	s_cselect_b32 s30, s47, s45
	s_cselect_b32 s31, s46, s44
	s_ashr_i32 s39, s38, 31
	s_lshl_b64 s[6:7], s[38:39], 20
	s_add_u32 s48, s36, s6
	s_addc_u32 s49, s37, s7
	s_and_b64 s[6:7], vcc, exec
	s_cselect_b32 s39, s49, s5
	s_cselect_b32 s43, s48, s4
	s_add_u32 s64, s31, 0x80
	s_addc_u32 s65, s30, 0
	s_add_u32 s6, s44, 0x80080
	s_addc_u32 s7, s45, 0
	s_add_u32 s66, s4, 0x100
	v_mov_b32_e32 v2, 0
	s_addc_u32 s67, s5, 0
	s_mov_b32 s68, -2
	s_mov_b64 s[4:5], 0
	v_mov_b32_e32 v3, v2
	v_mov_b32_e32 v4, v2
	v_mov_b32_e32 v5, v2
	v_mov_b32_e32 v6, v2
	v_mov_b32_e32 v7, v2
	v_mov_b32_e32 v8, v2
	v_mov_b32_e32 v9, v2
	v_mov_b32_e32 v10, v2
	v_mov_b32_e32 v11, v2
	v_mov_b32_e32 v12, v2
	v_mov_b32_e32 v13, v2
	v_mov_b32_e32 v14, v2
	v_mov_b32_e32 v15, v2
	v_mov_b32_e32 v16, v2
	v_mov_b32_e32 v17, v2
	v_mov_b32_e32 v26, v2
	v_mov_b32_e32 v27, v2
	v_mov_b32_e32 v28, v2
	v_mov_b32_e32 v29, v2
	v_mov_b32_e32 v30, v2
	v_mov_b32_e32 v31, v2
	v_mov_b32_e32 v32, v2
	v_mov_b32_e32 v33, v2
	v_mov_b32_e32 v42, v2
	v_mov_b32_e32 v43, v2
	v_mov_b32_e32 v44, v2
	v_mov_b32_e32 v45, v2
	v_mov_b32_e32 v46, v2
	v_mov_b32_e32 v47, v2
	v_mov_b32_e32 v48, v2
	v_mov_b32_e32 v49, v2
	v_mov_b32_e32 v18, v2
	v_mov_b32_e32 v19, v2
	v_mov_b32_e32 v20, v2
	v_mov_b32_e32 v21, v2
	v_mov_b32_e32 v22, v2
	v_mov_b32_e32 v23, v2
	v_mov_b32_e32 v24, v2
	v_mov_b32_e32 v25, v2
	v_mov_b32_e32 v34, v2
	v_mov_b32_e32 v35, v2
	v_mov_b32_e32 v36, v2
	v_mov_b32_e32 v37, v2
	v_mov_b32_e32 v38, v2
	v_mov_b32_e32 v39, v2
	v_mov_b32_e32 v40, v2
	v_mov_b32_e32 v41, v2
	v_mov_b32_e32 v50, v2
	v_mov_b32_e32 v51, v2
	v_mov_b32_e32 v52, v2
	v_mov_b32_e32 v53, v2
	v_mov_b32_e32 v54, v2
	v_mov_b32_e32 v55, v2
	v_mov_b32_e32 v56, v2
	v_mov_b32_e32 v57, v2
	v_mov_b32_e32 v58, v2
	v_mov_b32_e32 v59, v2
	v_mov_b32_e32 v60, v2
	v_mov_b32_e32 v61, v2
	v_mov_b32_e32 v62, v2
	v_mov_b32_e32 v63, v2
	v_mov_b32_e32 v64, v2
	v_mov_b32_e32 v65, v2
	v_mov_b32_e32 v66, v2
	v_mov_b32_e32 v67, v2
	v_mov_b32_e32 v68, v2
	v_mov_b32_e32 v69, v2
	v_mov_b32_e32 v70, v2
	v_mov_b32_e32 v71, v2
	v_mov_b32_e32 v72, v2
	v_mov_b32_e32 v73, v2
	v_mov_b32_e32 v74, v2
	v_mov_b32_e32 v75, v2
	v_mov_b32_e32 v76, v2
	v_mov_b32_e32 v77, v2
	v_mov_b32_e32 v78, v2
	v_mov_b32_e32 v79, v2
	v_mov_b32_e32 v80, v2
	v_mov_b32_e32 v81, v2
	v_mov_b32_e32 v90, v2
	v_mov_b32_e32 v91, v2
	v_mov_b32_e32 v92, v2
	v_mov_b32_e32 v93, v2
	v_mov_b32_e32 v94, v2
	v_mov_b32_e32 v95, v2
	v_mov_b32_e32 v96, v2
	v_mov_b32_e32 v97, v2
	v_mov_b32_e32 v106, v2
	v_mov_b32_e32 v107, v2
	v_mov_b32_e32 v108, v2
	v_mov_b32_e32 v109, v2
	v_mov_b32_e32 v110, v2
	v_mov_b32_e32 v111, v2
	v_mov_b32_e32 v112, v2
	v_mov_b32_e32 v113, v2
	v_mov_b32_e32 v82, v2
	v_mov_b32_e32 v83, v2
	v_mov_b32_e32 v84, v2
	v_mov_b32_e32 v85, v2
	v_mov_b32_e32 v86, v2
	v_mov_b32_e32 v87, v2
	v_mov_b32_e32 v88, v2
	v_mov_b32_e32 v89, v2
	v_mov_b32_e32 v98, v2
	v_mov_b32_e32 v99, v2
	v_mov_b32_e32 v100, v2
	v_mov_b32_e32 v101, v2
	v_mov_b32_e32 v102, v2
	v_mov_b32_e32 v103, v2
	v_mov_b32_e32 v104, v2
	v_mov_b32_e32 v105, v2
	v_mov_b32_e32 v114, v2
	v_mov_b32_e32 v115, v2
	v_mov_b32_e32 v116, v2
	v_mov_b32_e32 v117, v2
	v_mov_b32_e32 v118, v2
	v_mov_b32_e32 v119, v2
	v_mov_b32_e32 v120, v2
	v_mov_b32_e32 v121, v2
	v_mov_b32_e32 v122, v2
	v_mov_b32_e32 v123, v2
	v_mov_b32_e32 v124, v2
	v_mov_b32_e32 v125, v2
	v_mov_b32_e32 v126, v2
	v_mov_b32_e32 v127, v2
	v_mov_b32_e32 v128, v2
	v_mov_b32_e32 v129, v2
	v_lshl_add_u64 v[144:145], s[6:7], 0, v[138:139]
	v_lshl_add_u64 v[146:147], s[6:7], 0, v[140:141]
	s_add_u32 s6, s44, s4
	s_addc_u32 s7, s45, s5
	s_add_u32 s8, s6, 0x100
	s_addc_u32 s9, s7, 0
	s_add_u32 s69, s66, s4
	s_addc_u32 s78, s67, s5
	s_add_u32 s86, s6, 0x180
	s_addc_u32 s87, s7, 0
	s_cmpk_eq_i32 s4, 0xf00
	s_cselect_b32 s51, s30, s9
	s_cselect_b32 s50, s31, s8
	s_cselect_b32 s7, s39, s78
	s_cselect_b32 s6, s43, s69
	s_cselect_b32 s9, s65, s87
	s_cselect_b32 s8, s64, s86
	s_add_u32 s86, s44, s4
	s_addc_u32 s87, s45, s5
	s_add_u32 s86, s86, 0x80080
	s_addc_u32 s87, s87, 0
.LBB0_62:
	s_add_i32 s69, 0, 0x10000
	v_add_u32_e32 v152, s69, v150
	ds_read_b128 v[158:161], v152
	ds_read_b128 v[162:165], v152 offset:1024
	ds_read_b128 v[166:169], v152 offset:2048
	ds_read_b128 v[178:181], v152 offset:3072
	s_add_i32 m0, s41, 0xc000
	ds_read_b128 v[182:185], v151
	ds_read_b128 v[186:189], v151 offset:1024
	ds_read_b128 v[190:193], v151 offset:2048
	ds_read_b128 v[194:197], v151 offset:3072
	ds_read_b128 v[198:201], v151 offset:4096
	ds_read_b128 v[202:205], v151 offset:5120
	ds_read_b128 v[206:209], v151 offset:6144
	ds_read_b128 v[210:213], v151 offset:7168
	global_load_lds_dwordx4 v138, s[86:87]
	s_add_i32 m0, s41, 0xe000
	s_nop 0
	global_load_lds_dwordx4 v140, s[86:87]
	s_waitcnt lgkmcnt(8)
	s_barrier
	s_waitcnt lgkmcnt(0)
	s_setprio 1
	s_waitcnt lgkmcnt(0)
	v_mfma_f32_16x16x32_bf16 v[126:129], v[158:161], v[182:185], v[126:129]
	v_mfma_f32_16x16x32_bf16 v[122:125], v[166:169], v[182:185], v[122:125]
	v_mfma_f32_16x16x32_bf16 v[118:121], v[158:161], v[190:193], v[118:121]
	v_mfma_f32_16x16x32_bf16 v[114:117], v[166:169], v[190:193], v[114:117]
	v_mfma_f32_16x16x32_bf16 v[102:105], v[158:161], v[198:201], v[102:105]
	v_mfma_f32_16x16x32_bf16 v[98:101], v[166:169], v[198:201], v[98:101]
	v_mfma_f32_16x16x32_bf16 v[86:89], v[158:161], v[206:209], v[86:89]
	v_mfma_f32_16x16x32_bf16 v[82:85], v[166:169], v[206:209], v[82:85]
	v_mfma_f32_16x16x32_bf16 v[126:129], v[162:165], v[186:189], v[126:129]
	v_mfma_f32_16x16x32_bf16 v[122:125], v[178:181], v[186:189], v[122:125]
	v_mfma_f32_16x16x32_bf16 v[118:121], v[162:165], v[194:197], v[118:121]
	v_mfma_f32_16x16x32_bf16 v[114:117], v[178:181], v[194:197], v[114:117]
	v_mfma_f32_16x16x32_bf16 v[102:105], v[162:165], v[202:205], v[102:105]
	v_mfma_f32_16x16x32_bf16 v[98:101], v[178:181], v[202:205], v[98:101]
	v_mfma_f32_16x16x32_bf16 v[86:89], v[162:165], v[210:213], v[86:89]
	v_mfma_f32_16x16x32_bf16 v[82:85], v[178:181], v[210:213], v[82:85]
	s_setprio 0
	s_barrier
; #define PG8_STAGE(bufoff, gbase, voff) do { _Pragma("unroll") for (int _i = 0; _i < 2; ++_i) \
;         __builtin_amdgcn_global_load_lds((const unsigned*)((const char*)(gbase) + (voff)[_i]), (LAS unsigned*)(lds + (bufoff) + ldsw + _i * 8192), 16, 0, 0); } while (0)
; #define PG8_LDA(dst, b, h) do { _Pragma("unroll") for (int m = 0; m < 4; ++m) _Pragma("unroll") for (int k = 0; k < 2; ++k) dst[m][k] = *(const LAS bf16x8*)(lds + PG8_SA(b, h) + aoff + m * 2048 + k * 1024); } while (0)
; #define PG8_LDB(dst, b, h) do { _Pragma("unroll") for (int n = 0; n < 2; ++n) _Pragma("unroll") for (int k = 0; k < 2; ++k) dst[n][k] = *(const LAS bf16x8*)(lds + PG8_SB(b, h) + boff + n * 2048 + k * 1024); } while (0)
; #define PG8_MMA(ai, bj, At, Bt) do { __builtin_amdgcn_s_setprio(1); _Pragma("unroll") for (int m = 0; m < 4; ++m) _Pragma("unroll") for (int n = 0; n < 2; ++n) _Pragma("unroll") for (int k = 0; k < 2; ++k) \
;         acc[ai][bj][m][n] = __builtin_amdgcn_mfma_f32_16x16x32_bf16(Bt[n][k], At[m][k], acc[ai][bj][m][n], 0, 0, 0); __builtin_amdgcn_s_setprio(0); } while (0)
; #define PG8_WAIT_V(n) asm volatile("s_waitcnt vmcnt(" #n ")" ::: "memory")
; #define PG8_WAIT_L(n) asm volatile("s_waitcnt lgkmcnt(" #n ")" ::: "memory")
; #define PG8_BAR __builtin_amdgcn_s_barrier()
; #define PG8_SCHED __builtin_amdgcn_sched_barrier(0)
; template <class Epi>
; DI void gemm_phase(LAS unsigned char* lds, const Gemm g, const StaticOrder& S, const Epi& E, const int tid) {
;     ...
;             PG8_LDB(B1, 0, 1); PG8_STAGE(PG8_SB(0, 0), b2, voffB);
;             PG8_BAR; PG8_WAIT_L(0); PG8_MMA(0, 1, At, B1); PG8_BAR;
;             PG8_LDA(At, 0, 1); PG8_STAGE(PG8_SA(0, 0), a2, voffA);
;             PG8_BAR; PG8_WAIT_L(0); PG8_MMA(1, 0, At, B0); PG8_BAR; PG8_SCHED;
;             PG8_STAGE(PG8_SB(0, 1), b2 + hstepB, voffB);
;             PG8_WAIT_V(6); PG8_BAR; PG8_MMA(1, 1, At, B1); PG8_BAR;
;             PG8_LDB(B0, 1, 0); PG8_SCHED; PG8_LDA(At, 1, 0); PG8_STAGE(PG8_SA(0, 1), a2 + hstepA, voffA);
;             PG8_WAIT_L(8); PG8_BAR; PG8_WAIT_L(0); PG8_MMA(0, 0, At, B0); PG8_BAR; PG8_SCHED;
	s_add_i32 s78, 0, 0x14000
	v_add_u32_e32 v152, s78, v150
	s_add_i32 s69, s69, s26
	ds_read_b128 v[214:217], v152
	ds_read_b128 v[218:221], v152 offset:1024
	ds_read_b128 v[222:225], v152 offset:2048
	ds_read_b128 v[226:229], v152 offset:3072
	s_mov_b32 m0, s69
	s_nop 0
	global_load_lds_dwordx4 v0, s[6:7]
	s_add_i32 m0, s69, 0x2000
	s_nop 0
	global_load_lds_dwordx4 v130, s[6:7]
	s_barrier
	s_waitcnt lgkmcnt(0)
	s_setprio 1
	s_waitcnt lgkmcnt(0)
	v_mfma_f32_16x16x32_bf16 v[110:113], v[214:217], v[182:185], v[110:113]
	v_mfma_f32_16x16x32_bf16 v[106:109], v[222:225], v[182:185], v[106:109]
	v_mfma_f32_16x16x32_bf16 v[94:97], v[214:217], v[190:193], v[94:97]
	v_mfma_f32_16x16x32_bf16 v[90:93], v[222:225], v[190:193], v[90:93]
	v_mfma_f32_16x16x32_bf16 v[78:81], v[214:217], v[198:201], v[78:81]
	v_mfma_f32_16x16x32_bf16 v[74:77], v[222:225], v[198:201], v[74:77]
	v_mfma_f32_16x16x32_bf16 v[70:73], v[214:217], v[206:209], v[70:73]
	v_mfma_f32_16x16x32_bf16 v[66:69], v[222:225], v[206:209], v[66:69]
	v_mfma_f32_16x16x32_bf16 v[110:113], v[218:221], v[186:189], v[110:113]
	v_mfma_f32_16x16x32_bf16 v[106:109], v[226:229], v[186:189], v[106:109]
	v_mfma_f32_16x16x32_bf16 v[94:97], v[218:221], v[194:197], v[94:97]
	v_mfma_f32_16x16x32_bf16 v[90:93], v[226:229], v[194:197], v[90:93]
	v_mfma_f32_16x16x32_bf16 v[78:81], v[218:221], v[202:205], v[78:81]
	v_mfma_f32_16x16x32_bf16 v[74:77], v[226:229], v[202:205], v[74:77]
	v_mfma_f32_16x16x32_bf16 v[70:73], v[218:221], v[210:213], v[70:73]
	v_mfma_f32_16x16x32_bf16 v[66:69], v[226:229], v[210:213], v[66:69]
	s_setprio 0
	s_mov_b32 m0, s41
	s_barrier
	ds_read_b128 v[182:185], v151 offset:16384
	ds_read_b128 v[186:189], v151 offset:17408
	ds_read_b128 v[190:193], v151 offset:18432
	ds_read_b128 v[194:197], v151 offset:19456
	ds_read_b128 v[198:201], v151 offset:20480
	ds_read_b128 v[202:205], v151 offset:21504
	ds_read_b128 v[206:209], v151 offset:22528
	ds_read_b128 v[210:213], v151 offset:23552
	global_load_lds_dwordx4 v134, s[50:51]
	s_mov_b32 m0, s55
	s_nop 0
	global_load_lds_dwordx4 v132, s[50:51]
	s_barrier
	s_waitcnt lgkmcnt(0)
	s_setprio 1
	s_waitcnt lgkmcnt(0)
	v_mfma_f32_16x16x32_bf16 v[62:65], v[158:161], v[182:185], v[62:65]
	v_mfma_f32_16x16x32_bf16 v[58:61], v[166:169], v[182:185], v[58:61]
	v_mfma_f32_16x16x32_bf16 v[54:57], v[158:161], v[190:193], v[54:57]
	v_mfma_f32_16x16x32_bf16 v[50:53], v[166:169], v[190:193], v[50:53]
	v_mfma_f32_16x16x32_bf16 v[38:41], v[158:161], v[198:201], v[38:41]
	v_mfma_f32_16x16x32_bf16 v[34:37], v[166:169], v[198:201], v[34:37]
	v_mfma_f32_16x16x32_bf16 v[22:25], v[158:161], v[206:209], v[22:25]
	v_mfma_f32_16x16x32_bf16 v[18:21], v[166:169], v[206:209], v[18:21]
	v_mfma_f32_16x16x32_bf16 v[62:65], v[162:165], v[186:189], v[62:65]
	v_mfma_f32_16x16x32_bf16 v[58:61], v[178:181], v[186:189], v[58:61]
	v_mfma_f32_16x16x32_bf16 v[54:57], v[162:165], v[194:197], v[54:57]
	v_mfma_f32_16x16x32_bf16 v[50:53], v[178:181], v[194:197], v[50:53]
	v_mfma_f32_16x16x32_bf16 v[38:41], v[162:165], v[202:205], v[38:41]
	v_mfma_f32_16x16x32_bf16 v[34:37], v[178:181], v[202:205], v[34:37]
	v_mfma_f32_16x16x32_bf16 v[22:25], v[162:165], v[210:213], v[22:25]
	v_mfma_f32_16x16x32_bf16 v[18:21], v[178:181], v[210:213], v[18:21]
	s_setprio 0
	s_barrier
	s_add_u32 s86, s6, 0x80000
	s_addc_u32 s87, s7, 0
	s_add_i32 s69, s78, s26
	s_mov_b32 m0, s69
	s_nop 0
	global_load_lds_dwordx4 v0, s[86:87]
	s_add_i32 m0, s69, 0x2000
	s_nop 0
	global_load_lds_dwordx4 v130, s[86:87]
	s_waitcnt vmcnt(6)
	s_barrier
	s_setprio 1
	v_mfma_f32_16x16x32_bf16 v[46:49], v[214:217], v[182:185], v[46:49]
	v_mfma_f32_16x16x32_bf16 v[42:45], v[222:225], v[182:185], v[42:45]
	v_mfma_f32_16x16x32_bf16 v[30:33], v[214:217], v[190:193], v[30:33]
	v_mfma_f32_16x16x32_bf16 v[26:29], v[222:225], v[190:193], v[26:29]
	v_mfma_f32_16x16x32_bf16 v[14:17], v[214:217], v[198:201], v[14:17]
	v_mfma_f32_16x16x32_bf16 v[10:13], v[222:225], v[198:201], v[10:13]
	v_mfma_f32_16x16x32_bf16 v[6:9], v[214:217], v[206:209], v[6:9]
	v_mfma_f32_16x16x32_bf16 v[2:5], v[222:225], v[206:209], v[2:5]
	v_mfma_f32_16x16x32_bf16 v[46:49], v[218:221], v[186:189], v[46:49]
	v_mfma_f32_16x16x32_bf16 v[42:45], v[226:229], v[186:189], v[42:45]
	v_mfma_f32_16x16x32_bf16 v[30:33], v[218:221], v[194:197], v[30:33]
	v_mfma_f32_16x16x32_bf16 v[26:29], v[226:229], v[194:197], v[26:29]
	v_mfma_f32_16x16x32_bf16 v[14:17], v[218:221], v[202:205], v[14:17]
	v_mfma_f32_16x16x32_bf16 v[10:13], v[226:229], v[202:205], v[10:13]
	v_mfma_f32_16x16x32_bf16 v[6:9], v[218:221], v[210:213], v[6:9]
	v_mfma_f32_16x16x32_bf16 v[2:5], v[226:229], v[210:213], v[2:5]
	s_setprio 0
	s_add_i32 s69, 0, 0x18000
	v_add_u32_e32 v173, s69, v150
	s_barrier
	ds_read_b128 v[158:161], v173
	ds_read_b128 v[162:165], v173 offset:1024
	ds_read_b128 v[166:169], v173 offset:2048
	ds_read_b128 v[178:181], v173 offset:3072
	s_add_u32 s50, s50, 0x80000
	s_addc_u32 s51, s51, 0
	s_mov_b32 m0, s56
	s_nop 0
	ds_read_b128 v[182:185], v151 offset:32768
	ds_read_b128 v[186:189], v151 offset:33792
	ds_read_b128 v[190:193], v151 offset:34816
	ds_read_b128 v[194:197], v151 offset:35840
	ds_read_b128 v[198:201], v151 offset:36864
	ds_read_b128 v[202:205], v151 offset:37888
	ds_read_b128 v[206:209], v151 offset:38912
	ds_read_b128 v[210:213], v151 offset:39936
	global_load_lds_dwordx4 v134, s[50:51]
	s_mov_b32 m0, s57
	s_nop 0
	global_load_lds_dwordx4 v132, s[50:51]
	s_waitcnt lgkmcnt(8)
	s_barrier
; #define PG8_STAGE(bufoff, gbase, voff) do { _Pragma("unroll") for (int _i = 0; _i < 2; ++_i) \
;         __builtin_amdgcn_global_load_lds((const unsigned*)((const char*)(gbase) + (voff)[_i]), (LAS unsigned*)(lds + (bufoff) + ldsw + _i * 8192), 16, 0, 0); } while (0)
; #define PG8_LDA(dst, b, h) do { _Pragma("unroll") for (int m = 0; m < 4; ++m) _Pragma("unroll") for (int k = 0; k < 2; ++k) dst[m][k] = *(const LAS bf16x8*)(lds + PG8_SA(b, h) + aoff + m * 2048 + k * 1024); } while (0)
; #define PG8_LDB(dst, b, h) do { _Pragma("unroll") for (int n = 0; n < 2; ++n) _Pragma("unroll") for (int k = 0; k < 2; ++k) dst[n][k] = *(const LAS bf16x8*)(lds + PG8_SB(b, h) + boff + n * 2048 + k * 1024); } while (0)
; #define PG8_MMA(ai, bj, At, Bt) do { __builtin_amdgcn_s_setprio(1); _Pragma("unroll") for (int m = 0; m < 4; ++m) _Pragma("unroll") for (int n = 0; n < 2; ++n) _Pragma("unroll") for (int k = 0; k < 2; ++k) \
;         acc[ai][bj][m][n] = __builtin_amdgcn_mfma_f32_16x16x32_bf16(Bt[n][k], At[m][k], acc[ai][bj][m][n], 0, 0, 0); __builtin_amdgcn_s_setprio(0); } while (0)
; #define PG8_WAIT_V(n) asm volatile("s_waitcnt vmcnt(" #n ")" ::: "memory")
; #define PG8_WAIT_L(n) asm volatile("s_waitcnt lgkmcnt(" #n ")" ::: "memory")
; #define PG8_BAR __builtin_amdgcn_s_barrier()
; #define PG8_SCHED __builtin_amdgcn_sched_barrier(0)
; template <class Epi>
; DI void gemm_phase(LAS unsigned char* lds, const Gemm g, const StaticOrder& S, const Epi& E, const int tid) {
;     ...
;             const bool last = (t == nt - 2);
;             const char* a1 = cA + PG8_KTA(t + 1);
;             const char* a2 = last ? nA : cA + PG8_KTA(t + 2); const char* b2 = last ? nB : cB + (size_t)(t + 2) * kstep;
;             const char* a3 = last ? nA + PG8_KTA(1) : cA + PG8_KTA(t + 3); const char* b3 = b2 + kstep;
;     ...
;             PG8_WAIT_L(8); PG8_BAR; PG8_WAIT_L(0); PG8_MMA(0, 0, At, B0); PG8_BAR; PG8_SCHED;
;             PG8_LDB(B1, 1, 1); PG8_STAGE(PG8_SB(1, 0), b3, voffB);
;             PG8_BAR; PG8_WAIT_L(0); PG8_MMA(0, 1, At, B1); PG8_BAR;
;             PG8_LDA(At, 1, 1); PG8_STAGE(PG8_SA(1, 0), a3, voffA);
;             PG8_BAR; PG8_WAIT_L(0); PG8_MMA(1, 0, At, B0); PG8_BAR; PG8_SCHED;
;             PG8_STAGE(PG8_SB(1, 1), b3 + hstepB, voffB);
;             PG8_WAIT_V(6); PG8_BAR; PG8_MMA(1, 1, At, B1); PG8_BAR;
	s_waitcnt lgkmcnt(0)
	s_setprio 1
	s_waitcnt lgkmcnt(0)
	v_mfma_f32_16x16x32_bf16 v[126:129], v[158:161], v[182:185], v[126:129]
	v_mfma_f32_16x16x32_bf16 v[122:125], v[166:169], v[182:185], v[122:125]
	v_mfma_f32_16x16x32_bf16 v[118:121], v[158:161], v[190:193], v[118:121]
	v_mfma_f32_16x16x32_bf16 v[114:117], v[166:169], v[190:193], v[114:117]
	v_mfma_f32_16x16x32_bf16 v[102:105], v[158:161], v[198:201], v[102:105]
	v_mfma_f32_16x16x32_bf16 v[98:101], v[166:169], v[198:201], v[98:101]
	v_mfma_f32_16x16x32_bf16 v[86:89], v[158:161], v[206:209], v[86:89]
	v_mfma_f32_16x16x32_bf16 v[82:85], v[166:169], v[206:209], v[82:85]
	v_mfma_f32_16x16x32_bf16 v[126:129], v[162:165], v[186:189], v[126:129]
	v_mfma_f32_16x16x32_bf16 v[122:125], v[178:181], v[186:189], v[122:125]
	v_mfma_f32_16x16x32_bf16 v[118:121], v[162:165], v[194:197], v[118:121]
	v_mfma_f32_16x16x32_bf16 v[114:117], v[178:181], v[194:197], v[114:117]
	v_mfma_f32_16x16x32_bf16 v[102:105], v[162:165], v[202:205], v[102:105]
	v_mfma_f32_16x16x32_bf16 v[98:101], v[178:181], v[202:205], v[98:101]
	v_mfma_f32_16x16x32_bf16 v[86:89], v[162:165], v[210:213], v[86:89]
	v_mfma_f32_16x16x32_bf16 v[82:85], v[178:181], v[210:213], v[82:85]
	s_setprio 0
	s_barrier
	s_add_i32 s50, 0, 0x1c000
	s_add_i32 s51, s69, s26
	v_add_u32_e32 v173, s50, v150
	s_add_u32 s86, s6, s84
	s_addc_u32 s87, s7, s85
	s_mov_b32 m0, s51
	ds_read_b128 v[214:217], v173
	ds_read_b128 v[218:221], v173 offset:1024
	ds_read_b128 v[222:225], v173 offset:2048
	ds_read_b128 v[226:229], v173 offset:3072
	global_load_lds_dwordx4 v0, s[86:87]
	s_add_i32 m0, s51, 0x2000
	s_nop 0
	global_load_lds_dwordx4 v130, s[86:87]
	s_barrier
	s_waitcnt lgkmcnt(0)
	s_setprio 1
	s_waitcnt lgkmcnt(0)
	v_mfma_f32_16x16x32_bf16 v[110:113], v[214:217], v[182:185], v[110:113]
	v_mfma_f32_16x16x32_bf16 v[106:109], v[222:225], v[182:185], v[106:109]
	v_mfma_f32_16x16x32_bf16 v[94:97], v[214:217], v[190:193], v[94:97]
	v_mfma_f32_16x16x32_bf16 v[90:93], v[222:225], v[190:193], v[90:93]
	v_mfma_f32_16x16x32_bf16 v[78:81], v[214:217], v[198:201], v[78:81]
	v_mfma_f32_16x16x32_bf16 v[74:77], v[222:225], v[198:201], v[74:77]
	v_mfma_f32_16x16x32_bf16 v[70:73], v[214:217], v[206:209], v[70:73]
	v_mfma_f32_16x16x32_bf16 v[66:69], v[222:225], v[206:209], v[66:69]
	v_mfma_f32_16x16x32_bf16 v[110:113], v[218:221], v[186:189], v[110:113]
	v_mfma_f32_16x16x32_bf16 v[106:109], v[226:229], v[186:189], v[106:109]
	v_mfma_f32_16x16x32_bf16 v[94:97], v[218:221], v[194:197], v[94:97]
	v_mfma_f32_16x16x32_bf16 v[90:93], v[226:229], v[194:197], v[90:93]
	v_mfma_f32_16x16x32_bf16 v[78:81], v[218:221], v[202:205], v[78:81]
	v_mfma_f32_16x16x32_bf16 v[74:77], v[226:229], v[202:205], v[74:77]
	v_mfma_f32_16x16x32_bf16 v[70:73], v[218:221], v[210:213], v[70:73]
	v_mfma_f32_16x16x32_bf16 v[66:69], v[226:229], v[210:213], v[66:69]
	s_setprio 0
	s_mov_b32 m0, s59
	s_nop 0
	s_barrier
	ds_read_b128 v[182:185], v151 offset:49152
	ds_read_b128 v[186:189], v151 offset:50176
	ds_read_b128 v[190:193], v151 offset:51200
	ds_read_b128 v[194:197], v151 offset:52224
	ds_read_b128 v[198:201], v151 offset:53248
	ds_read_b128 v[202:205], v151 offset:54272
	ds_read_b128 v[206:209], v151 offset:55296
	ds_read_b128 v[210:213], v151 offset:56320
	global_load_lds_dwordx4 v134, s[8:9]
	s_mov_b32 m0, s60
	s_nop 0
	global_load_lds_dwordx4 v132, s[8:9]
	s_barrier
	s_waitcnt lgkmcnt(0)
	s_setprio 1
	s_waitcnt lgkmcnt(0)
	v_mfma_f32_16x16x32_bf16 v[62:65], v[158:161], v[182:185], v[62:65]
	v_mfma_f32_16x16x32_bf16 v[58:61], v[166:169], v[182:185], v[58:61]
	v_mfma_f32_16x16x32_bf16 v[54:57], v[158:161], v[190:193], v[54:57]
	v_mfma_f32_16x16x32_bf16 v[50:53], v[166:169], v[190:193], v[50:53]
	v_mfma_f32_16x16x32_bf16 v[38:41], v[158:161], v[198:201], v[38:41]
	v_mfma_f32_16x16x32_bf16 v[34:37], v[166:169], v[198:201], v[34:37]
	v_mfma_f32_16x16x32_bf16 v[22:25], v[158:161], v[206:209], v[22:25]
	v_mfma_f32_16x16x32_bf16 v[18:21], v[166:169], v[206:209], v[18:21]
	v_mfma_f32_16x16x32_bf16 v[62:65], v[162:165], v[186:189], v[62:65]
	v_mfma_f32_16x16x32_bf16 v[58:61], v[178:181], v[186:189], v[58:61]
	v_mfma_f32_16x16x32_bf16 v[54:57], v[162:165], v[194:197], v[54:57]
	v_mfma_f32_16x16x32_bf16 v[50:53], v[178:181], v[194:197], v[50:53]
	v_mfma_f32_16x16x32_bf16 v[38:41], v[162:165], v[202:205], v[38:41]
	v_mfma_f32_16x16x32_bf16 v[34:37], v[178:181], v[202:205], v[34:37]
	v_mfma_f32_16x16x32_bf16 v[22:25], v[162:165], v[210:213], v[22:25]
	v_mfma_f32_16x16x32_bf16 v[18:21], v[178:181], v[210:213], v[18:21]
	s_setprio 0
	s_barrier
	s_add_u32 s6, s6, 0x80080
	s_addc_u32 s7, s7, 0
	s_add_i32 s8, s50, s26
	s_mov_b32 m0, s8
	s_nop 0
	global_load_lds_dwordx4 v0, s[6:7]
	s_add_i32 m0, s8, 0x2000
	s_nop 0
	global_load_lds_dwordx4 v130, s[6:7]
	s_waitcnt vmcnt(6)
	s_barrier
	s_setprio 1
	v_mfma_f32_16x16x32_bf16 v[46:49], v[214:217], v[182:185], v[46:49]
	v_mfma_f32_16x16x32_bf16 v[42:45], v[222:225], v[182:185], v[42:45]
	v_mfma_f32_16x16x32_bf16 v[30:33], v[214:217], v[190:193], v[30:33]
	v_mfma_f32_16x16x32_bf16 v[26:29], v[222:225], v[190:193], v[26:29]
	v_mfma_f32_16x16x32_bf16 v[14:17], v[214:217], v[198:201], v[14:17]
	v_mfma_f32_16x16x32_bf16 v[10:13], v[222:225], v[198:201], v[10:13]
	v_mfma_f32_16x16x32_bf16 v[6:9], v[214:217], v[206:209], v[6:9]
	v_mfma_f32_16x16x32_bf16 v[2:5], v[222:225], v[206:209], v[2:5]
	v_mfma_f32_16x16x32_bf16 v[46:49], v[218:221], v[186:189], v[46:49]
	v_mfma_f32_16x16x32_bf16 v[42:45], v[226:229], v[186:189], v[42:45]
	v_mfma_f32_16x16x32_bf16 v[30:33], v[218:221], v[194:197], v[30:33]
	v_mfma_f32_16x16x32_bf16 v[26:29], v[226:229], v[194:197], v[26:29]
	v_mfma_f32_16x16x32_bf16 v[14:17], v[218:221], v[202:205], v[14:17]
	v_mfma_f32_16x16x32_bf16 v[10:13], v[226:229], v[202:205], v[10:13]
	v_mfma_f32_16x16x32_bf16 v[6:9], v[218:221], v[210:213], v[6:9]
	v_mfma_f32_16x16x32_bf16 v[2:5], v[226:229], v[210:213], v[2:5]
	s_setprio 0
	s_add_i32 s68, s68, 2
	s_add_u32 s4, s4, 0x100
	s_addc_u32 s5, s5, 0
	s_add_u32 s6, s44, s4
	s_addc_u32 s7, s45, s5
	s_add_u32 s8, s6, 0x100
	s_addc_u32 s9, s7, 0
	s_add_u32 s69, s66, s4
	s_addc_u32 s78, s67, s5
	s_add_u32 s86, s6, 0x180
	s_addc_u32 s87, s7, 0
	s_cmpk_eq_i32 s4, 0xf00
	s_cselect_b32 s51, s30, s9
	s_cselect_b32 s50, s31, s8
	s_cselect_b32 s7, s39, s78
	s_cselect_b32 s6, s43, s69
	s_cselect_b32 s9, s65, s87
	s_cselect_b32 s8, s64, s86
	s_add_u32 s86, s44, s4
	s_addc_u32 s87, s45, s5
	s_add_u32 s86, s86, 0x80080
	s_addc_u32 s87, s87, 0
	s_cmp_gt_u32 s68, 29
	s_barrier
; DI unsigned pk2(float a, float b) { f32x2 v = {a, b}; bf16v2 r = __builtin_convertvector(v, bf16v2); return __builtin_bit_cast(unsigned, r); }
; #define PG8_WAIT_V(n) asm volatile("s_waitcnt vmcnt(" #n ")" ::: "memory")
;     DI void operator()(const f32x4 (&acc)[2][2][4][2], const Unit& u, int wr, int wc, int fr, int fq) const {
;         if (nt) {
;             unsigned char* tb = (unsigned char*)O + ((size_t)(u.pm * nt + u.pn) << 17) + (wr * 4 + wc) * 1024 + (fq * 16 + fr) * 16;
; #pragma unroll
;             for (int ai = 0; ai < 2; ++ai)
; #pragma unroll
;                 for (int m = 0; m < 4; ++m)
; #pragma unroll
;                     for (int bj = 0; bj < 2; ++bj) { const f32x4 v0 = acc[ai][bj][m][0], v1 = acc[ai][bj][m][1];
;                         u32x4 w; w.x = pk2(v0[0], v0[1]); w.y = pk2(v0[2], v0[3]); w.z = pk2(v1[0], v1[1]); w.w = pk2(v1[2], v1[3]);
;                         *(u32x4*)(tb + ((ai * 4 + m) * 2 + bj) * 8192) = w; }
;             return;
; template <class Epi>
; DI void gemm_phase(LAS unsigned char* lds, const Gemm g, const StaticOrder& S, const Epi& E, const int tid) {
;     ...
;         E(acc, cur, wr, wc, fr, fq);
;         if (!has_next) break;
; #pragma unroll
;         for (int a = 0; a < 2; ++a)
; #pragma unroll
;             for (int b = 0; b < 2; ++b)
; #pragma unroll
;                 for (int m = 0; m < 4; ++m)
; #pragma unroll
;                     for (int n = 0; n < 2; ++n) acc[a][b][m][n] = (f32x4){0.f, 0.f, 0.f, 0.f};
;         cur = nxt; cA = nA; cB = nB; ++ui;
;     }
;     PG8_WAIT_V(0);
	s_cbranch_scc0 .LBB0_62
	s_mul_i32 s4, s40, s58
	s_add_i32 s4, s4, s63
	s_ashr_i32 s5, s4, 31
	s_lshl_b64 s[4:5], s[4:5], 17
	v_lshl_add_u64 v[144:145], v[136:137], 0, s[4:5]
	s_movk_i32 s4, 0x2000
	v_cvt_pk_bf16_f32 v110, v110, v111
	v_cvt_pk_bf16_f32 v111, v112, v113
	v_cvt_pk_bf16_f32 v112, v106, v107
	v_add_co_u32_e32 v106, vcc, s4, v144
	v_cvt_pk_bf16_f32 v113, v108, v109
	s_nop 0
	v_addc_co_u32_e32 v107, vcc, 0, v145, vcc
	global_store_dwordx4 v[106:107], v[110:113], off
	s_movk_i32 s4, 0x6000
	v_cvt_pk_bf16_f32 v94, v94, v95
	v_add_co_u32_e32 v110, vcc, s3, v144
	v_cvt_pk_bf16_f32 v95, v96, v97
	s_nop 0
	v_addc_co_u32_e32 v111, vcc, 0, v145, vcc
	v_cvt_pk_bf16_f32 v96, v90, v91
	v_add_co_u32_e32 v90, vcc, s4, v144
	v_cvt_pk_bf16_f32 v97, v92, v93
	s_nop 0
	v_addc_co_u32_e32 v91, vcc, 0, v145, vcc
	s_mov_b32 s4, 0x8000
	global_store_dwordx4 v[90:91], v[94:97], off
	v_cvt_pk_bf16_f32 v78, v78, v79
	v_cvt_pk_bf16_f32 v79, v80, v81
	v_add_co_u32_e32 v94, vcc, s4, v144
	s_mov_b32 s4, 0xa000
	s_nop 0
	v_addc_co_u32_e32 v95, vcc, 0, v145, vcc
	v_cvt_pk_bf16_f32 v80, v74, v75
	v_add_co_u32_e32 v74, vcc, s4, v144
	v_cvt_pk_bf16_f32 v81, v76, v77
	s_nop 0
	v_addc_co_u32_e32 v75, vcc, 0, v145, vcc
	global_store_dwordx4 v[74:75], v[78:81], off
	s_mov_b32 s4, 0xe000
	v_cvt_pk_bf16_f32 v70, v70, v71
	v_add_co_u32_e32 v78, vcc, s13, v144
	v_cvt_pk_bf16_f32 v71, v72, v73
	s_nop 0
	v_addc_co_u32_e32 v79, vcc, 0, v145, vcc
	v_cvt_pk_bf16_f32 v72, v66, v67
	v_add_co_u32_e32 v66, vcc, s4, v144
	s_mov_b32 s4, 0x10000
	s_nop 0
	v_addc_co_u32_e32 v67, vcc, 0, v145, vcc
	v_cvt_pk_bf16_f32 v62, v62, v63
	v_cvt_pk_bf16_f32 v63, v64, v65
	v_cvt_pk_bf16_f32 v64, v58, v59
	v_add_co_u32_e32 v58, vcc, s4, v144
	s_mov_b32 s4, 0x12000
	s_nop 0
	v_addc_co_u32_e32 v59, vcc, 0, v145, vcc
	v_cvt_pk_bf16_f32 v46, v46, v47
	v_cvt_pk_bf16_f32 v47, v48, v49
	v_cvt_pk_bf16_f32 v48, v42, v43
	v_add_co_u32_e32 v42, vcc, s4, v144
	v_cvt_pk_bf16_f32 v49, v44, v45
	s_nop 0
	v_addc_co_u32_e32 v43, vcc, 0, v145, vcc
	s_mov_b32 s4, 0x14000
	global_store_dwordx4 v[42:43], v[46:49], off
	v_cvt_pk_bf16_f32 v30, v30, v31
	v_cvt_pk_bf16_f32 v31, v32, v33
	v_add_co_u32_e32 v46, vcc, s4, v144
	s_mov_b32 s4, 0x16000
	s_nop 0
	v_addc_co_u32_e32 v47, vcc, 0, v145, vcc
	v_cvt_pk_bf16_f32 v32, v26, v27
	v_add_co_u32_e32 v26, vcc, s4, v144
	v_cvt_pk_bf16_f32 v33, v28, v29
	s_nop 0
	v_addc_co_u32_e32 v27, vcc, 0, v145, vcc
	s_mov_b32 s4, 0x18000
	global_store_dwordx4 v[26:27], v[30:33], off
	v_cvt_pk_bf16_f32 v14, v14, v15
	v_cvt_pk_bf16_f32 v15, v16, v17
	v_add_co_u32_e32 v30, vcc, s4, v144
	s_mov_b32 s4, 0x1a000
	s_nop 0
	v_addc_co_u32_e32 v31, vcc, 0, v145, vcc
	v_cvt_pk_bf16_f32 v16, v10, v11
	v_add_co_u32_e32 v10, vcc, s4, v144
	v_cvt_pk_bf16_f32 v17, v12, v13
	s_nop 0
	v_addc_co_u32_e32 v11, vcc, 0, v145, vcc
	s_mov_b32 s4, 0x1c000
	global_store_dwordx4 v[10:11], v[14:17], off
	v_cvt_pk_bf16_f32 v6, v6, v7
	v_cvt_pk_bf16_f32 v7, v8, v9
	v_add_co_u32_e32 v14, vcc, s4, v144
	v_cvt_pk_bf16_f32 v8, v2, v3
	s_nop 0
	v_addc_co_u32_e32 v15, vcc, 0, v145, vcc
	v_add_co_u32_e32 v2, vcc, 0x1e000, v144
	v_cvt_pk_bf16_f32 v126, v126, v127
	s_nop 0
	v_addc_co_u32_e32 v3, vcc, 0, v145, vcc
	v_cvt_pk_bf16_f32 v127, v128, v129
	v_cvt_pk_bf16_f32 v128, v122, v123
	v_cvt_pk_bf16_f32 v129, v124, v125
	v_cvt_pk_bf16_f32 v106, v118, v119
	v_cvt_pk_bf16_f32 v107, v120, v121
	v_cvt_pk_bf16_f32 v108, v114, v115
	v_cvt_pk_bf16_f32 v109, v116, v117
	v_cvt_pk_bf16_f32 v90, v102, v103
	v_cvt_pk_bf16_f32 v91, v104, v105
	v_cvt_pk_bf16_f32 v92, v98, v99
	v_cvt_pk_bf16_f32 v93, v100, v101
	v_cvt_pk_bf16_f32 v74, v86, v87
	v_cvt_pk_bf16_f32 v75, v88, v89
	v_cvt_pk_bf16_f32 v76, v82, v83
	v_cvt_pk_bf16_f32 v77, v84, v85
	v_cvt_pk_bf16_f32 v73, v68, v69
	v_cvt_pk_bf16_f32 v65, v60, v61
	v_cvt_pk_bf16_f32 v42, v54, v55
	v_cvt_pk_bf16_f32 v43, v56, v57
	v_cvt_pk_bf16_f32 v44, v50, v51
	v_cvt_pk_bf16_f32 v45, v52, v53
	v_cvt_pk_bf16_f32 v26, v38, v39
	v_cvt_pk_bf16_f32 v27, v40, v41
	v_cvt_pk_bf16_f32 v28, v34, v35
	v_cvt_pk_bf16_f32 v29, v36, v37
	v_cvt_pk_bf16_f32 v10, v22, v23
	v_cvt_pk_bf16_f32 v11, v24, v25
	v_cvt_pk_bf16_f32 v12, v18, v19
	v_cvt_pk_bf16_f32 v13, v20, v21
	v_cvt_pk_bf16_f32 v9, v4, v5
	s_and_b64 vcc, exec, s[34:35]
	s_mov_b32 s63, s38
	s_mov_b32 s40, s42
	s_mov_b64 s[4:5], s[48:49]
	s_mov_b64 s[44:45], s[46:47]
	global_store_dwordx4 v[144:145], v[126:129], off
	global_store_dwordx4 v[110:111], v[106:109], off
	global_store_dwordx4 v[94:95], v[90:93], off
	global_store_dwordx4 v[78:79], v[74:77], off
	global_store_dwordx4 v[66:67], v[70:73], off
	global_store_dwordx4 v[58:59], v[62:65], off
	global_store_dwordx4 v[46:47], v[42:45], off
	global_store_dwordx4 v[30:31], v[26:29], off
	global_store_dwordx4 v[14:15], v[10:13], off
	global_store_dwordx4 v[2:3], v[6:9], off
	s_cbranch_vccz .LBB0_59
	s_waitcnt vmcnt(0)
	s_cmpk_gt_u32 s25, 0xff
	s_cbranch_scc1 .LBB0_66
	s_barrier
